# recurrence waves at s_setprio 2 with three nt decode waves beside them
# speedup vs baseline: 1.0208x; 1.0002x over previous
; __device__ __forceinline__ void scan_prompt_wave(const Params& P, unsigned char* lds, int b, int h, int quarter) {
;     ...
;     } else if (wave < 4) {
;         const int rl = quarter * 16 + wave * 4 + (lane >> 4), cl = lane & 15, c0 = cl * 4;
;         float* op = (float*)(P.ws + WS_ORAW) + (size_t)(b * SEQ) * RW + h * 64 + rl;
;         float4 S = make_float4(0.f, 0.f, 0.f, 0.f);
;         while (scw[0] < 1u) __builtin_amdgcn_s_sleep(1);
;         asm volatile("" ::: "memory");
;         StepIn r[4];
;         lds_load_step(r[0], (const float*)lds, c0, rl); lds_load_step(r[1], (const float*)lds + RSB_BLK, c0, rl); lds_load_step(r[2], (const float*)lds + 2 * RSB_BLK, c0, rl);
.LBB0_1226:
	s_setprio 2
	s_lshr_b32 s0, s56, 3
	s_and_b32 s0, s0, 3
	s_lshl_b32 s0, s0, 4
	s_lshl_b32 s3, s2, 2
	s_or_b32 s0, s3, s0
	v_lshrrev_b32_e32 v2, 4, v1
	v_or_b32_e32 v2, s0, v2
	v_lshlrev_b32_e32 v115, 2, v2
	v_and_b32_e32 v3, 15, v1
	v_lshlrev_b32_e32 v114, 4, v3
	v_and_b32_e32 v121, 3, v1
	v_bfe_u32 v124, v1, 2, 2
	v_lshl_add_u32 v124, v121, 2, v124
	v_mul_u32_u24_e32 v117, 0x610, v124
	v_add_u32_e32 v116, v117, v115
	v_cmp_eq_u32_e64 s[8:9], 1, v121
	v_cmp_eq_u32_e64 s[10:11], 2, v121
	v_cmp_eq_u32_e64 s[12:13], 3, v121
	s_mul_i32 s14, s33, 0x600000
	s_add_u32 s14, s78, s14
	s_addc_u32 s15, s79, 0
	s_lshl_b32 s16, s40, 8
	s_add_u32 s14, s14, s16
	s_addc_u32 s15, s15, 0
	s_add_u32 s14, s14, 0x1349cc00
	s_addc_u32 s15, s15, 0
	v_mul_u32_u24_e32 v124, 0x600, v124
	v_add_u32_e32 v124, v124, v115
	v_mov_b32_e32 v125, 0
	v_lshl_add_u64 v[122:123], s[14:15], 0, v[124:125]
	v_mov_b32_e32 v118, s41
	s_lshl_b32 s16, s2, 2
	s_add_i32 s16, s16, 0x23004
	v_mov_b32_e32 v119, s16
	s_mov_b32 s4, 0
	s_movk_i32 s5, 0x7000
	s_mov_b32 s42, 0
	s_mov_b32 s6, 2
	s_mov_b64 s[0:1], 0x6000
	v_mov_b32_e32 v4, 0
	v_mov_b32_e32 v5, 0
	v_mov_b32_e32 v6, 0
	v_mov_b32_e32 v7, 0
	v_mov_b32_e32 v110, v114
	v_mov_b32_e32 v111, v115
	v_add_u32_e32 v112, s5, v114
	v_add_u32_e32 v113, s5, v115
	ds_read_b128 v[8:11], v110
	ds_read_b128 v[24:27], v110 offset:1024
	ds_read_b32 v28, v111 offset:1280
	ds_read_b128 v[20:23], v110 offset:768
	ds_read_b128 v[16:19], v110 offset:512
	ds_read_b128 v[30:33], v110 offset:1552
	ds_read_b128 v[46:49], v110 offset:2576
	ds_read_b32 v50, v111 offset:2832
	ds_read_b128 v[42:45], v110 offset:2320
	ds_read_b128 v[38:41], v110 offset:2064
	ds_read_b128 v[52:55], v110 offset:3104
	ds_read_b128 v[68:71], v110 offset:4128
	ds_read_b32 v72, v111 offset:4384
	ds_read_b128 v[64:67], v110 offset:3872
	ds_read_b128 v[60:63], v110 offset:3616

; __device__ __forceinline__ void scan_prompt_wave(const Params& P, unsigned char* lds, int b, int h, int quarter) {
;     ...
;         for (int c = 0; c < NCH; ++c) {
;             const float* bp = (const float*)(lds + (c % SC_NB) * SC_BUF); const float* bpn = (const float*)(lds + ((c + 1) % SC_NB) * SC_BUF);
;             float ov = 0.f;
; #pragma unroll
;             for (int s = 0; s < SCH; ++s) {
;                 if (s == SCH - 3 && c + 1 < NCH) { while (scw[0] < (unsigned)(c + 2)) __builtin_amdgcn_s_sleep(1); asm volatile("" ::: "memory"); }
;                 lds_load_step(r[(s + 3) & 3], (s + 3 < SCH) ? bp + (s + 3) * RSB_BLK : bpn + (s + 3 - SCH) * RSB_BLK, c0, rl); __builtin_amdgcn_sched_barrier(0);
;                 const float o = scan_step_asm(S, r[s & 3]); __builtin_amdgcn_sched_barrier(0);
;                 ov = (cl == s) ? o : ov;
;             }
;             op[(size_t)cl * RW] = ov;
;             op += (size_t)SCH * RW;
;             if (lane == 0) scw[1 + wave] = (unsigned)(c + 1);
;         }
;         *(float4*)(P.out + OUT_WKV_P + ((size_t)(b * RH + h) * HD + rl) * HD + c0) = S;
.Lscan_landed:
	ds_read_b128 v[8:11], v112
	ds_read_b128 v[24:27], v112 offset:1024
	ds_read_b32 v28, v113 offset:1280
	ds_read_b128 v[20:23], v112 offset:768
	ds_read_b128 v[16:19], v112 offset:512
	v_mul_f32_e32 v108, v4, v30
	v_fmac_f32_e32 v108, v5, v31
	v_fmac_f32_e32 v108, v6, v32
	v_fmac_f32_e32 v108, v7, v33
	v_mul_f32_e32 v97, v4, v46
	v_fmac_f32_e32 v97, v5, v47
	v_add_f32_dpp v108, v108, v108 quad_perm:[1,0,3,2] row_mask:0xf bank_mask:0xf
	v_fmac_f32_e32 v97, v6, v48
	v_fmac_f32_e32 v97, v7, v49
	v_add_f32_dpp v108, v108, v108 quad_perm:[2,3,0,1] row_mask:0xf bank_mask:0xf
	v_fmac_f32_e32 v4, v50, v42
	v_fmac_f32_e32 v5, v50, v43
	v_add_f32_dpp v108, v108, v108 row_ror:4 row_mask:0xf bank_mask:0xf
	v_fmac_f32_e32 v6, v50, v44
	v_fmac_f32_e32 v7, v50, v45
	v_add_f32_dpp v108, v108, v108 row_ror:8 row_mask:0xf bank_mask:0xf
	v_fma_f32 v4, -v108, v38, v4
	v_fma_f32 v5, -v108, v39, v5
	v_fma_f32 v6, -v108, v40, v6
	v_fma_f32 v7, -v108, v41, v7
	s_waitcnt lgkmcnt(8)
	ds_read_b128 v[30:33], v112 offset:1552
	ds_read_b128 v[46:49], v112 offset:2576
	ds_read_b32 v50, v113 offset:2832
	ds_read_b128 v[42:45], v112 offset:2320
	ds_read_b128 v[38:41], v112 offset:2064
	v_mul_f32_e32 v108, v4, v52
	v_fmac_f32_e32 v108, v5, v53
	v_fmac_f32_e32 v108, v6, v54
	v_fmac_f32_e32 v108, v7, v55
	v_mul_f32_e32 v98, v4, v68
	v_fmac_f32_e32 v98, v5, v69
	v_add_f32_dpp v108, v108, v108 quad_perm:[1,0,3,2] row_mask:0xf bank_mask:0xf
	v_fmac_f32_e32 v98, v6, v70
	v_fmac_f32_e32 v98, v7, v71
	v_add_f32_dpp v108, v108, v108 quad_perm:[2,3,0,1] row_mask:0xf bank_mask:0xf
	v_fmac_f32_e32 v4, v72, v64
	v_fmac_f32_e32 v5, v72, v65
	v_add_f32_dpp v108, v108, v108 row_ror:4 row_mask:0xf bank_mask:0xf
	v_fmac_f32_e32 v6, v72, v66
	v_fmac_f32_e32 v7, v72, v67
	v_add_f32_dpp v108, v108, v108 row_ror:8 row_mask:0xf bank_mask:0xf
	v_fma_f32 v4, -v108, v60, v4
	v_fma_f32 v5, -v108, v61, v5
	v_fma_f32 v6, -v108, v62, v6
	v_fma_f32 v7, -v108, v63, v7
	ds_read_b128 v[52:55], v112 offset:3104
	ds_read_b128 v[68:71], v112 offset:4128
	ds_read_b32 v72, v113 offset:4384
	ds_read_b128 v[64:67], v112 offset:3872
	ds_read_b128 v[60:63], v112 offset:3616
	v_mul_f32_e32 v108, v4, v74
	v_fmac_f32_e32 v108, v5, v75
	v_fmac_f32_e32 v108, v6, v76
	v_fmac_f32_e32 v108, v7, v77
	v_mul_f32_e32 v99, v4, v90
	v_fmac_f32_e32 v99, v5, v91
	v_add_f32_dpp v108, v108, v108 quad_perm:[1,0,3,2] row_mask:0xf bank_mask:0xf
	v_fmac_f32_e32 v99, v6, v92
	v_fmac_f32_e32 v99, v7, v93
	v_add_f32_dpp v108, v108, v108 quad_perm:[2,3,0,1] row_mask:0xf bank_mask:0xf
	v_add_f32_dpp v100, v96, v96 row_ror:8 row_mask:0xf bank_mask:0x3
	v_add_f32_dpp v100, v98, v98 row_ror:8 row_mask:0xf bank_mask:0xc
	v_add_f32_dpp v108, v108, v108 row_ror:4 row_mask:0xf bank_mask:0xf
	v_add_f32_dpp v101, v97, v97 row_ror:8 row_mask:0xf bank_mask:0x3
	v_add_f32_dpp v101, v99, v99 row_ror:8 row_mask:0xf bank_mask:0xc
	v_add_f32_dpp v108, v108, v108 row_ror:8 row_mask:0xf bank_mask:0xf
	v_fmac_f32_e32 v4, v94, v86
	v_fmac_f32_e32 v5, v94, v87
	v_add_f32_dpp v105, v100, v100 row_half_mirror row_mask:0xf bank_mask:0x5
	v_add_f32_dpp v105, v101, v101 row_half_mirror row_mask:0xf bank_mask:0xa
	v_fmac_f32_e32 v6, v94, v88
	v_fmac_f32_e32 v7, v94, v89
	v_add_f32_dpp v105, v105, v105 quad_perm:[1,0,3,2] row_mask:0xf bank_mask:0xf
	v_fma_f32 v4, -v108, v82, v4
	v_fma_f32 v5, -v108, v83, v5
	v_fma_f32 v6, -v108, v84, v6
	v_fma_f32 v7, -v108, v85, v7
	v_add_f32_dpp v105, v105, v105 quad_perm:[2,3,0,1] row_mask:0xf bank_mask:0xf
	v_mul_f32_e32 v4, v4, v78
	v_mul_f32_e32 v5, v5, v79
	v_mul_f32_e32 v6, v6, v80
	v_mul_f32_e32 v7, v7, v81
	v_cndmask_b32_e64 v102, v102, v103, s[8:9]
	v_cndmask_b32_e64 v102, v102, v104, s[10:11]
	s_add_i32 s42, s42, 1
	s_mov_b32 s4, s5
	s_add_i32 s5, s5, 0x7000
	v_cndmask_b32_e64 v102, v102, v105, s[12:13]
	s_waitcnt lgkmcnt(15)
	s_cmp_eq_u32 s5, 0x23000
	s_cselect_b32 s5, 0, s5
	v_fmac_f32_e32 v102, v106, v107
	s_add_i32 s6, s42, 2
	s_min_u32 s6, s6, 0x100
	global_store_dword v[122:123], v102, off
	v_mov_b32_e32 v110, v112
	v_mov_b32_e32 v111, v113
	v_add_u32_e32 v112, s5, v114
	v_add_u32_e32 v113, s5, v115
	v_lshl_add_u64 v[122:123], v[122:123], 0, s[0:1]
	s_cmpk_lg_i32 s42, 0x100
	s_cbranch_scc1 .Lscan_chunk
	s_waitcnt lgkmcnt(0)
	v_mov_b32_e32 v2, v4
	v_mov_b32_e32 v98, v5
	v_mov_b32_e32 v99, v6
	v_mov_b32_e32 v100, v7
	v_lshrrev_b32_e32 v88, 2, v115
	v_mov_b32_e32 v89, 0
	v_lshrrev_b32_e32 v3, 2, v114
	s_setprio 0
	s_branch .LBB0_1249
